# phase0 prep_weights transpose items: 8 loads in flight per item instead of load-wait-write x8
# speedup vs baseline: 1.0132x; 1.0012x over previous
; #define LAS __attribute__((address_space(3)))
; __device__ __forceinline__ unsigned pk2(float lo, float hi) { f32x2 v = {lo, hi}; bf16x2_t b = __builtin_convertvector(v, bf16x2_t); return __builtin_bit_cast(unsigned, b); }
; #define WAVE_LDS_FENCE() asm volatile("s_waitcnt lgkmcnt(0)" ::: "memory")
; template <int MODE>
; __device__ __forceinline__ void transpose_item(const float* W, int K, int Nsrc, const float* g, bf16_t* WT, LAS float* scr, int kb, int nb, int lane) {
;     ...
;     WAVE_LDS_FENCE();
;     const int c = lane & 7;
; #pragma unroll
;     for (int j = 0; j < 4; ++j) { const int n = (lane >> 3) + 8 * j; const LAS float* s = scr + (8 * c) * 33 + n;
;         u32x4 o; o.x = pk2(s[0 * 33], s[1 * 33]); o.y = pk2(s[2 * 33], s[3 * 33]); o.z = pk2(s[4 * 33], s[5 * 33]); o.w = pk2(s[6 * 33], s[7 * 33]);
;         *(u32x4*)(WT + (size_t)(n0 + n) * K + k0 + 8 * c) = o; }
;     WAVE_LDS_FENCE();
.LBB0_10:
	s_waitcnt lgkmcnt(0)
	ds_read2_b32 v[24:25], v35 offset0:33 offset1:41
	ds_read2_b32 v[26:27], v35 offset1:8
	ds_read2_b32 v[52:53], v35 offset0:66 offset1:74
	ds_read2_b32 v[54:55], v35 offset0:99 offset1:107
	ds_read2_b32 v[56:57], v35 offset0:132 offset1:140
	ds_read2_b32 v[58:59], v35 offset0:165 offset1:173
	ds_read2_b32 v[60:61], v35 offset0:198 offset1:206
	ds_read2_b32 v[62:63], v35 offset0:231 offset1:239
	v_add_u32_e32 v66, s30, v8
	s_ashr_i32 s39, s38, 31
	v_ashrrev_i32_e32 v67, 31, v66
	v_lshl_add_u64 v[64:65], s[38:39], 1, v[12:13]
	v_lshlrev_b64 v[68:69], 11, v[66:67]
	s_waitcnt lgkmcnt(6)
	v_cvt_pk_bf16_f32 v2, v26, v24
	s_waitcnt lgkmcnt(4)
	v_cvt_pk_bf16_f32 v3, v52, v54
	s_waitcnt lgkmcnt(2)
	v_cvt_pk_bf16_f32 v4, v56, v58
	s_waitcnt lgkmcnt(0)
	v_cvt_pk_bf16_f32 v5, v60, v62
	v_lshl_add_u64 v[68:69], v[64:65], 0, v[68:69]
	v_add_u32_e32 v24, 8, v66
	global_store_dwordx4 v[68:69], v[2:5], off
	s_nop 1
	v_cvt_pk_bf16_f32 v2, v27, v25
	v_ashrrev_i32_e32 v25, 31, v24
	v_cvt_pk_bf16_f32 v3, v53, v55
	v_cvt_pk_bf16_f32 v4, v57, v59
	v_cvt_pk_bf16_f32 v5, v61, v63
	v_lshlrev_b64 v[24:25], 11, v[24:25]
	ds_read2_b32 v[26:27], v35 offset0:49 offset1:57
	ds_read2_b32 v[52:53], v35 offset0:16 offset1:24
	ds_read2_b32 v[54:55], v35 offset0:82 offset1:90
	ds_read2_b32 v[56:57], v35 offset0:115 offset1:123
	ds_read2_b32 v[58:59], v35 offset0:148 offset1:156
	ds_read2_b32 v[60:61], v35 offset0:181 offset1:189
	ds_read2_b32 v[62:63], v35 offset0:214 offset1:222
	ds_read2_b32 v[68:69], v35 offset0:247 offset1:255
	v_lshl_add_u64 v[24:25], v[64:65], 0, v[24:25]
	global_store_dwordx4 v[24:25], v[2:5], off
	v_add_u32_e32 v24, 16, v66
	v_ashrrev_i32_e32 v25, 31, v24
	v_lshlrev_b64 v[24:25], 11, v[24:25]
	s_waitcnt lgkmcnt(6)
	v_cvt_pk_bf16_f32 v2, v52, v26
	s_waitcnt lgkmcnt(4)
	v_cvt_pk_bf16_f32 v3, v54, v56
	s_waitcnt lgkmcnt(2)
	v_cvt_pk_bf16_f32 v4, v58, v60
	s_waitcnt lgkmcnt(0)
	v_cvt_pk_bf16_f32 v5, v62, v68
	v_lshl_add_u64 v[24:25], v[64:65], 0, v[24:25]
	global_store_dwordx4 v[24:25], v[2:5], off
	v_add_u32_e32 v24, 24, v66
	v_ashrrev_i32_e32 v25, 31, v24
	v_lshlrev_b64 v[24:25], 11, v[24:25]
	v_cvt_pk_bf16_f32 v2, v53, v27
	v_cvt_pk_bf16_f32 v3, v55, v57
	v_cvt_pk_bf16_f32 v4, v59, v61
	v_cvt_pk_bf16_f32 v5, v63, v69
	v_lshl_add_u64 v[24:25], v[64:65], 0, v[24:25]
	global_store_dwordx4 v[24:25], v[2:5], off
	s_waitcnt lgkmcnt(0)

; #define LAS __attribute__((address_space(3)))
; __device__ __forceinline__ unsigned pk2(float lo, float hi) { f32x2 v = {lo, hi}; bf16x2_t b = __builtin_convertvector(v, bf16x2_t); return __builtin_bit_cast(unsigned, b); }
; #define WAVE_LDS_FENCE() asm volatile("s_waitcnt lgkmcnt(0)" ::: "memory")
; template <int MODE>
; __device__ __forceinline__ void transpose_item(const float* W, int K, int Nsrc, const float* g, bf16_t* WT, LAS float* scr, int kb, int nb, int lane) {
;     ...
;     for (int i = 0; i < 8; ++i) { const int kk = 8 * i + (lane >> 3); f32x4 v = {0.f, 0.f, 0.f, 0.f};
;         if (src >= 0) { v = *(const f32x4*)(W + (size_t)(k0 + kk) * Nsrc + src); if (g) v = v * g[k0 + kk]; }
;         LAS float* d = scr + kk * 33 + (lane & 7) * 4; d[0] = v[0]; d[1] = v[1]; d[2] = v[2]; d[3] = v[3]; }
;     WAVE_LDS_FENCE();
;     const int c = lane & 7;
; #pragma unroll
;     for (int j = 0; j < 4; ++j) { const int n = (lane >> 3) + 8 * j; const LAS float* s = scr + (8 * c) * 33 + n;
;         u32x4 o; o.x = pk2(s[0 * 33], s[1 * 33]); o.y = pk2(s[2 * 33], s[3 * 33]); o.z = pk2(s[4 * 33], s[5 * 33]); o.w = pk2(s[6 * 33], s[7 * 33]);
;         *(u32x4*)(WT + (size_t)(n0 + n) * K + k0 + 8 * c) = o; }
;     WAVE_LDS_FENCE();
; __device__ __forceinline__ void prep_weights(const Ctx& P, LAS unsigned char* lds, int l, int gw, int NGW) {
;     ...
;         transpose_item<0>(p_wdn + (size_t)l * DFF * D, DFF, D, nullptr, (bf16_t*)(ws + WS_WDN) + (size_t)l * D * DFF, scr, r / 32, r % 32, lane);
.LBB0_12:
	s_cmpk_gt_i32 s50, 0xe7f
	s_mov_b64 s[0:1], -1
	s_cbranch_scc0 .LBB0_46
	s_cmpk_gt_u32 s50, 0x107f
	s_cbranch_scc0 .LBB0_43
	s_cmpk_gt_u32 s50, 0x127f
	s_cbranch_scc0 .LBB0_40
	s_cmpk_gt_u32 s50, 0x147f
	s_cbranch_scc0 .LBB0_37
	s_cmpk_gt_u32 s50, 0x207f
	s_cbranch_scc0 .LBB0_18
	s_and_b32 s0, s45, 0x7fffffc0
	s_add_i32 s30, s0, 0xffffbf00
	s_and_b32 s0, s43, 0x3e0
	v_or_b32_e32 v2, s0, v1
	v_lshlrev_b32_e32 v10, 2, v2
	v_or_b32_e32 v2, s30, v8
	v_lshl_add_u64 v[24:25], s[28:29], 0, v[10:11]
	v_lshlrev_b32_e32 v10, 10, v2
	v_lshl_add_u64 v[2:3], v[10:11], 2, v[24:25]
	global_load_dwordx4 v[88:91], v[2:3], off
	v_or_b32_e32 v10, s30, v28
	v_lshlrev_b32_e32 v10, 10, v10
	v_lshl_add_u64 v[26:27], v[10:11], 2, v[24:25]
	v_or_b32_e32 v10, s30, v29
	v_lshlrev_b32_e32 v10, 10, v10
	v_or_b32_e32 v51, s0, v30
	v_mul_u32_u24_e32 v51, 0xc00, v51
	global_load_dwordx4 v[92:95], v[26:27], off
	v_lshl_add_u64 v[26:27], v[10:11], 2, v[24:25]
	v_or_b32_e32 v10, s30, v30
	v_lshlrev_b32_e32 v10, 10, v10
	global_load_dwordx4 v[96:99], v[26:27], off
	v_lshl_add_u64 v[26:27], v[10:11], 2, v[24:25]
	v_or_b32_e32 v10, s30, v31
	v_lshlrev_b32_e32 v10, 10, v10
	global_load_dwordx4 v[100:103], v[26:27], off
	v_lshl_add_u64 v[26:27], v[10:11], 2, v[24:25]
	v_or_b32_e32 v10, s30, v32
	v_lshlrev_b32_e32 v10, 10, v10
	global_load_dwordx4 v[104:107], v[26:27], off
	v_lshl_add_u64 v[26:27], v[10:11], 2, v[24:25]
	v_or_b32_e32 v10, s30, v33
	v_lshlrev_b32_e32 v10, 10, v10
	global_load_dwordx4 v[108:111], v[26:27], off
	v_lshl_add_u64 v[26:27], v[10:11], 2, v[24:25]
	v_or_b32_e32 v10, s30, v34
	v_lshlrev_b32_e32 v10, 10, v10
	v_lshl_add_u64 v[24:25], v[10:11], 2, v[24:25]
	v_or_b32_e32 v10, s0, v8
	v_mul_u32_u24_e32 v10, 0xc00, v10
	v_lshlrev_b32_e32 v10, 1, v10
	global_load_dwordx4 v[112:115], v[26:27], off
	v_or_b32_e32 v26, s0, v28
	v_or_b32_e32 v27, s0, v29
	v_mul_u32_u24_e32 v26, 0xc00, v26
	v_mul_u32_u24_e32 v27, 0xc00, v27
	s_mov_b64 s[0:1], 0
	global_load_dwordx4 v[116:119], v[24:25], off
	v_lshl_add_u64 v[24:25], s[30:31], 1, v[14:15]
	v_lshl_add_u64 v[60:61], v[24:25], 0, v[10:11]
	v_lshlrev_b32_e32 v10, 1, v26
	v_lshl_add_u64 v[62:63], v[24:25], 0, v[10:11]
	v_lshlrev_b32_e32 v10, 1, v27
	v_lshl_add_u64 v[64:65], v[24:25], 0, v[10:11]
	v_lshlrev_b32_e32 v10, 1, v51
	v_lshl_add_u64 v[66:67], v[24:25], 0, v[10:11]
	s_waitcnt vmcnt(0)
	ds_write2_b32 v36, v88, v89 offset1:1
	ds_write2_b32 v36, v90, v91 offset0:2 offset1:3
	ds_write2_b32 v37, v92, v93 offset1:1
	ds_write2_b32 v38, v94, v95 offset1:1
	ds_write2_b32 v39, v96, v97 offset1:1
	ds_write2_b32 v40, v98, v99 offset1:1
	ds_write2_b32 v41, v100, v101 offset1:1
	ds_write2_b32 v42, v102, v103 offset1:1
	ds_write2_b32 v43, v104, v105 offset1:1
	ds_write2_b32 v44, v106, v107 offset1:1
	ds_write2_b32 v45, v108, v109 offset1:1
	ds_write2_b32 v46, v110, v111 offset1:1
	ds_write2_b32 v47, v112, v113 offset1:1
	ds_write2_b32 v48, v114, v115 offset1:1
	ds_write2_b32 v49, v116, v117 offset1:1
	ds_write2_b32 v50, v118, v119 offset1:1
	s_waitcnt lgkmcnt(0)
	ds_read2_b32 v[24:25], v35 offset0:33 offset1:41
	ds_read2_b32 v[26:27], v35 offset1:8
	ds_read2_b32 v[52:53], v35 offset0:66 offset1:74
	ds_read2_b32 v[54:55], v35 offset0:99 offset1:107
	ds_read2_b32 v[56:57], v35 offset0:132 offset1:140
	ds_read2_b32 v[58:59], v35 offset0:165 offset1:173
	ds_read2_b32 v[68:69], v35 offset0:198 offset1:206
	ds_read2_b32 v[70:71], v35 offset0:231 offset1:239
	ds_read2_b32 v[72:73], v35 offset0:16 offset1:24
	ds_read2_b32 v[74:75], v35 offset0:49 offset1:57
	ds_read2_b32 v[76:77], v35 offset0:82 offset1:90
	ds_read2_b32 v[78:79], v35 offset0:115 offset1:123
	ds_read2_b32 v[80:81], v35 offset0:148 offset1:156
	ds_read2_b32 v[82:83], v35 offset0:181 offset1:189
	ds_read2_b32 v[84:85], v35 offset0:214 offset1:222
	ds_read2_b32 v[86:87], v35 offset0:247 offset1:255
	s_waitcnt lgkmcnt(14)
	v_cvt_pk_bf16_f32 v2, v26, v24
	s_waitcnt lgkmcnt(12)
	v_cvt_pk_bf16_f32 v3, v52, v54
	s_waitcnt lgkmcnt(10)
	v_cvt_pk_bf16_f32 v4, v56, v58
	s_waitcnt lgkmcnt(8)
	v_cvt_pk_bf16_f32 v5, v68, v70
	v_cvt_pk_bf16_f32 v24, v27, v25
	v_cvt_pk_bf16_f32 v25, v53, v55
	v_cvt_pk_bf16_f32 v26, v57, v59
	v_cvt_pk_bf16_f32 v27, v69, v71
	s_waitcnt lgkmcnt(6)
	v_cvt_pk_bf16_f32 v52, v72, v74
	s_waitcnt lgkmcnt(4)
	v_cvt_pk_bf16_f32 v53, v76, v78
	s_waitcnt lgkmcnt(2)
	v_cvt_pk_bf16_f32 v54, v80, v82
	s_waitcnt lgkmcnt(0)
	v_cvt_pk_bf16_f32 v55, v84, v86
	v_cvt_pk_bf16_f32 v56, v73, v75
	v_cvt_pk_bf16_f32 v57, v77, v79
	v_cvt_pk_bf16_f32 v58, v81, v83
	v_cvt_pk_bf16_f32 v59, v85, v87
	global_store_dwordx4 v[60:61], v[2:5], off
	global_store_dwordx4 v[62:63], v[24:27], off
	global_store_dwordx4 v[64:65], v[52:55], off
	global_store_dwordx4 v[66:67], v[56:59], off
	s_waitcnt lgkmcnt(0)
.LBB0_18:
	s_andn2_b64 vcc, exec, s[0:1]
	s_cbranch_vccnz .LBB0_36
	s_add_i32 s0, s50, 0xeb80
	s_and_b32 s1, s0, 0xffff
	s_mul_i32 s1, s1, 0xaaab
	s_lshr_b32 s1, s1, 23
	s_mul_i32 s4, s1, 0xc0
	s_sub_i32 s0, s0, s4
	s_lshl_b32 s0, s0, 5
	s_lshl_b32 s5, s1, 6
	s_and_b32 s4, s0, 0xffe0
	v_or_b32_e32 v2, s4, v1
	v_or_b32_e32 v26, s5, v8
	v_lshlrev_b32_e32 v10, 2, v2
	v_mul_u32_u24_e32 v2, 0x1800, v26
	v_lshl_add_u64 v[24:25], s[24:25], 0, v[10:11]
	v_lshlrev_b32_e32 v10, 2, v2
	v_lshl_add_u64 v[2:3], v[24:25], 0, v[10:11]
	global_load_dwordx4 v[88:91], v[2:3], off
	v_cndmask_b32_e64 v10, 0, 1, s[34:35]
	v_cmp_ne_u32_e64 s[0:1], 1, v10
	s_andn2_b64 vcc, exec, s[34:35]
	s_cbranch_vccnz .LBB0_21
	v_lshlrev_b32_e32 v10, 2, v26
	v_lshl_add_u64 v[26:27], s[26:27], 0, v[10:11]
	global_load_dword v144, v[26:27], off
; #define LAS __attribute__((address_space(3)))
; __device__ __forceinline__ unsigned pk2(float lo, float hi) { f32x2 v = {lo, hi}; bf16x2_t b = __builtin_convertvector(v, bf16x2_t); return __builtin_bit_cast(unsigned, b); }
; #define WAVE_LDS_FENCE() asm volatile("s_waitcnt lgkmcnt(0)" ::: "memory")
; template <int MODE>
; __device__ __forceinline__ void transpose_item(const float* W, int K, int Nsrc, const float* g, bf16_t* WT, LAS float* scr, int kb, int nb, int lane) {
;     ...
;     for (int i = 0; i < 8; ++i) { const int kk = 8 * i + (lane >> 3); f32x4 v = {0.f, 0.f, 0.f, 0.f};
;         if (src >= 0) { v = *(const f32x4*)(W + (size_t)(k0 + kk) * Nsrc + src); if (g) v = v * g[k0 + kk]; }
;         LAS float* d = scr + kk * 33 + (lane & 7) * 4; d[0] = v[0]; d[1] = v[1]; d[2] = v[2]; d[3] = v[3]; }
;     WAVE_LDS_FENCE();
;     const int c = lane & 7;
; #pragma unroll
;     for (int j = 0; j < 4; ++j) { const int n = (lane >> 3) + 8 * j; const LAS float* s = scr + (8 * c) * 33 + n;
;         u32x4 o; o.x = pk2(s[0 * 33], s[1 * 33]); o.y = pk2(s[2 * 33], s[3 * 33]); o.z = pk2(s[4 * 33], s[5 * 33]); o.w = pk2(s[6 * 33], s[7 * 33]);
;         *(u32x4*)(WT + (size_t)(n0 + n) * K + k0 + 8 * c) = o; }
;     WAVE_LDS_FENCE();
; __device__ __forceinline__ void prep_weights(const Ctx& P, LAS unsigned char* lds, int l, int gw, int NGW) {
;     ...
;         if (r < I_UP) { transpose_item<0>(p_wup + (size_t)l * D * DUP, D, DUP, p_g2 + l * D, (bf16_t*)(ws + WS_WUP) + (size_t)l * DUP * D, scr, r / 192, r % 192, lane); continue; } r -= I_UP;
.LBB0_21:
	v_or_b32_e32 v2, s5, v28
	v_mul_u32_u24_e32 v2, 0x1800, v2
	v_lshlrev_b32_e32 v10, 2, v2
	v_lshl_add_u64 v[2:3], v[24:25], 0, v[10:11]
	global_load_dwordx4 v[92:95], v[2:3], off
	s_and_b64 vcc, exec, s[0:1]
	v_add_lshl_u32 v26, v8, s5, 2
	s_cbranch_vccnz .LBB0_23
	v_mov_b32_e32 v27, v11
	v_lshl_add_u64 v[52:53], s[26:27], 0, v[26:27]
	global_load_dword v146, v[52:53], off offset:32
.LBB0_23:
	v_or_b32_e32 v2, s5, v29
	v_mul_u32_u24_e32 v2, 0x1800, v2
	v_lshlrev_b32_e32 v10, 2, v2
	v_lshl_add_u64 v[2:3], v[24:25], 0, v[10:11]
	global_load_dwordx4 v[96:99], v[2:3], off
	s_and_b64 vcc, exec, s[0:1]
	s_cbranch_vccnz .LBB0_25
	v_mov_b32_e32 v27, v11
	v_lshl_add_u64 v[52:53], s[26:27], 0, v[26:27]
	global_load_dword v148, v[52:53], off offset:64
.LBB0_25:
	v_or_b32_e32 v2, s5, v30
	v_mul_u32_u24_e32 v2, 0x1800, v2
	v_lshlrev_b32_e32 v10, 2, v2
	v_lshl_add_u64 v[2:3], v[24:25], 0, v[10:11]
	global_load_dwordx4 v[100:103], v[2:3], off
	s_and_b64 vcc, exec, s[0:1]
	s_cbranch_vccnz .LBB0_27
	v_mov_b32_e32 v27, v11
	v_lshl_add_u64 v[52:53], s[26:27], 0, v[26:27]
	global_load_dword v150, v[52:53], off offset:96
.LBB0_27:
	v_or_b32_e32 v2, s5, v31
	v_mul_u32_u24_e32 v2, 0x1800, v2
	v_lshlrev_b32_e32 v10, 2, v2
	v_lshl_add_u64 v[2:3], v[24:25], 0, v[10:11]
	global_load_dwordx4 v[104:107], v[2:3], off
	s_and_b64 vcc, exec, s[0:1]
	s_cbranch_vccnz .LBB0_29
	v_mov_b32_e32 v27, v11
	v_lshl_add_u64 v[52:53], s[26:27], 0, v[26:27]
	global_load_dword v152, v[52:53], off offset:128
.LBB0_29:
	v_or_b32_e32 v2, s5, v32
	v_mul_u32_u24_e32 v2, 0x1800, v2
	v_lshlrev_b32_e32 v10, 2, v2
	v_lshl_add_u64 v[2:3], v[24:25], 0, v[10:11]
	global_load_dwordx4 v[108:111], v[2:3], off
	s_and_b64 vcc, exec, s[0:1]
	s_cbranch_vccnz .LBB0_31
	v_mov_b32_e32 v27, v11
	v_lshl_add_u64 v[52:53], s[26:27], 0, v[26:27]
	global_load_dword v154, v[52:53], off offset:160
.LBB0_31:
	v_or_b32_e32 v2, s5, v33
	v_mul_u32_u24_e32 v2, 0x1800, v2
	v_lshlrev_b32_e32 v10, 2, v2
	v_lshl_add_u64 v[2:3], v[24:25], 0, v[10:11]
	global_load_dwordx4 v[112:115], v[2:3], off
	s_and_b64 vcc, exec, s[0:1]
	s_cbranch_vccnz .LBB0_33
	v_mov_b32_e32 v27, v11
	v_lshl_add_u64 v[52:53], s[26:27], 0, v[26:27]
	global_load_dword v156, v[52:53], off offset:192
.LBB0_33:
	v_or_b32_e32 v2, s5, v34
	v_mul_u32_u24_e32 v2, 0x1800, v2
	v_lshlrev_b32_e32 v10, 2, v2
	v_lshl_add_u64 v[2:3], v[24:25], 0, v[10:11]
	global_load_dwordx4 v[116:119], v[2:3], off
	s_and_b64 vcc, exec, s[0:1]
	s_cbranch_vccnz .LBB0_35
	v_mov_b32_e32 v27, v11
	v_lshl_add_u64 v[24:25], s[26:27], 0, v[26:27]
	global_load_dword v158, v[24:25], off offset:224
.LBB0_35:
	s_waitcnt vmcnt(0)
	s_and_b64 vcc, exec, s[0:1]
	s_cbranch_vccnz .Lpw_nomul_1
	v_pk_mul_f32 v[90:91], v[90:91], v[144:145] op_sel_hi:[1,0]
	v_pk_mul_f32 v[88:89], v[88:89], v[144:145] op_sel_hi:[1,0]
	v_pk_mul_f32 v[94:95], v[94:95], v[146:147] op_sel_hi:[1,0]
	v_pk_mul_f32 v[92:93], v[92:93], v[146:147] op_sel_hi:[1,0]
	v_pk_mul_f32 v[98:99], v[98:99], v[148:149] op_sel_hi:[1,0]
	v_pk_mul_f32 v[96:97], v[96:97], v[148:149] op_sel_hi:[1,0]
	v_pk_mul_f32 v[102:103], v[102:103], v[150:151] op_sel_hi:[1,0]
	v_pk_mul_f32 v[100:101], v[100:101], v[150:151] op_sel_hi:[1,0]
	v_pk_mul_f32 v[106:107], v[106:107], v[152:153] op_sel_hi:[1,0]
	v_pk_mul_f32 v[104:105], v[104:105], v[152:153] op_sel_hi:[1,0]
	v_pk_mul_f32 v[110:111], v[110:111], v[154:155] op_sel_hi:[1,0]
	v_pk_mul_f32 v[108:109], v[108:109], v[154:155] op_sel_hi:[1,0]
	v_pk_mul_f32 v[114:115], v[114:115], v[156:157] op_sel_hi:[1,0]
	v_pk_mul_f32 v[112:113], v[112:113], v[156:157] op_sel_hi:[1,0]
	v_pk_mul_f32 v[118:119], v[118:119], v[158:159] op_sel_hi:[1,0]
	v_pk_mul_f32 v[116:117], v[116:117], v[158:159] op_sel_hi:[1,0]
.Lpw_nomul_1:
	ds_write2_b32 v36, v88, v89 offset1:1
	ds_write2_b32 v36, v90, v91 offset0:2 offset1:3
	ds_write2_b32 v37, v92, v93 offset1:1
	ds_write2_b32 v38, v94, v95 offset1:1
	ds_write2_b32 v39, v96, v97 offset1:1
	ds_write2_b32 v40, v98, v99 offset1:1
	ds_write2_b32 v41, v100, v101 offset1:1
	ds_write2_b32 v42, v102, v103 offset1:1
	ds_write2_b32 v43, v104, v105 offset1:1
	ds_write2_b32 v44, v106, v107 offset1:1
	ds_write2_b32 v45, v108, v109 offset1:1
	ds_write2_b32 v46, v110, v111 offset1:1
	ds_write2_b32 v47, v112, v113 offset1:1
	ds_write2_b32 v48, v114, v115 offset1:1
	ds_write2_b32 v49, v116, v117 offset1:1
	ds_write2_b32 v50, v118, v119 offset1:1
	s_waitcnt lgkmcnt(0)
	ds_read2_b32 v[24:25], v35 offset0:33 offset1:41
	ds_read2_b32 v[26:27], v35 offset1:8
	ds_read2_b32 v[52:53], v35 offset0:66 offset1:74
	ds_read2_b32 v[54:55], v35 offset0:99 offset1:107
	ds_read2_b32 v[56:57], v35 offset0:132 offset1:140
	ds_read2_b32 v[58:59], v35 offset0:165 offset1:173
	ds_read2_b32 v[60:61], v35 offset0:198 offset1:206
	ds_read2_b32 v[62:63], v35 offset0:231 offset1:239
	s_lshl_b32 s30, s5, 1
	v_or_b32_e32 v10, s4, v8
	v_lshl_add_u64 v[64:65], v[16:17], 0, s[30:31]
	v_lshlrev_b32_e32 v10, 11, v10
	s_waitcnt lgkmcnt(6)
	v_cvt_pk_bf16_f32 v2, v26, v24
	s_waitcnt lgkmcnt(4)
	v_cvt_pk_bf16_f32 v3, v52, v54
	s_waitcnt lgkmcnt(2)
	v_cvt_pk_bf16_f32 v4, v56, v58
	s_waitcnt lgkmcnt(0)
	v_cvt_pk_bf16_f32 v5, v60, v62
	v_lshl_add_u64 v[66:67], v[64:65], 0, v[10:11]
	global_store_dwordx4 v[66:67], v[2:5], off
	v_or_b32_e32 v10, s4, v28
	v_lshlrev_b32_e32 v10, 11, v10
	v_cvt_pk_bf16_f32 v2, v27, v25
	v_cvt_pk_bf16_f32 v3, v53, v55
	v_cvt_pk_bf16_f32 v4, v57, v59
	v_cvt_pk_bf16_f32 v5, v61, v63
	ds_read2_b32 v[26:27], v35 offset0:49 offset1:57
	ds_read2_b32 v[52:53], v35 offset0:16 offset1:24
	ds_read2_b32 v[54:55], v35 offset0:82 offset1:90
	ds_read2_b32 v[56:57], v35 offset0:115 offset1:123
	ds_read2_b32 v[58:59], v35 offset0:148 offset1:156
	ds_read2_b32 v[60:61], v35 offset0:181 offset1:189
	ds_read2_b32 v[62:63], v35 offset0:214 offset1:222
	ds_read2_b32 v[66:67], v35 offset0:247 offset1:255
	v_lshl_add_u64 v[24:25], v[64:65], 0, v[10:11]
	v_or_b32_e32 v10, s4, v29
	v_lshlrev_b32_e32 v10, 11, v10
	global_store_dwordx4 v[24:25], v[2:5], off
	v_lshl_add_u64 v[24:25], v[64:65], 0, v[10:11]
	v_or_b32_e32 v10, s4, v30
	s_waitcnt lgkmcnt(6)
	v_cvt_pk_bf16_f32 v2, v52, v26
	s_waitcnt lgkmcnt(4)
	v_cvt_pk_bf16_f32 v3, v54, v56
	s_waitcnt lgkmcnt(2)
	v_cvt_pk_bf16_f32 v4, v58, v60
	s_waitcnt lgkmcnt(0)
	v_cvt_pk_bf16_f32 v5, v62, v66
	v_lshlrev_b32_e32 v10, 11, v10
	global_store_dwordx4 v[24:25], v[2:5], off
	v_lshl_add_u64 v[24:25], v[64:65], 0, v[10:11]
	s_nop 0
	v_cvt_pk_bf16_f32 v2, v53, v27
	v_cvt_pk_bf16_f32 v3, v55, v57
	v_cvt_pk_bf16_f32 v4, v59, v61
	v_cvt_pk_bf16_f32 v5, v63, v67
	global_store_dwordx4 v[24:25], v[2:5], off
	s_waitcnt lgkmcnt(0)

; #define LAS __attribute__((address_space(3)))
; __device__ __forceinline__ unsigned pk2(float lo, float hi) { f32x2 v = {lo, hi}; bf16x2_t b = __builtin_convertvector(v, bf16x2_t); return __builtin_bit_cast(unsigned, b); }
; #define WAVE_LDS_FENCE() asm volatile("s_waitcnt lgkmcnt(0)" ::: "memory")
; template <int MODE>
; __device__ __forceinline__ void transpose_item(const float* W, int K, int Nsrc, const float* g, bf16_t* WT, LAS float* scr, int kb, int nb, int lane) {
;     ...
;     for (int i = 0; i < 8; ++i) { const int kk = 8 * i + (lane >> 3); f32x4 v = {0.f, 0.f, 0.f, 0.f};
;         if (src >= 0) { v = *(const f32x4*)(W + (size_t)(k0 + kk) * Nsrc + src); if (g) v = v * g[k0 + kk]; }
;         LAS float* d = scr + kk * 33 + (lane & 7) * 4; d[0] = v[0]; d[1] = v[1]; d[2] = v[2]; d[3] = v[3]; }
;     WAVE_LDS_FENCE();
;     const int c = lane & 7;
; #pragma unroll
;     for (int j = 0; j < 4; ++j) { const int n = (lane >> 3) + 8 * j; const LAS float* s = scr + (8 * c) * 33 + n;
;         u32x4 o; o.x = pk2(s[0 * 33], s[1 * 33]); o.y = pk2(s[2 * 33], s[3 * 33]); o.z = pk2(s[4 * 33], s[5 * 33]); o.w = pk2(s[6 * 33], s[7 * 33]);
;         *(u32x4*)(WT + (size_t)(n0 + n) * K + k0 + 8 * c) = o; }
;     WAVE_LDS_FENCE();
; __device__ __forceinline__ void prep_weights(const Ctx& P, LAS unsigned char* lds, int l, int gw, int NGW) {
;     ...
;         if (r < I_SQ) { transpose_item<0>(p_wo + (size_t)l * D * D, D, D, nullptr, (bf16_t*)(ws + WS_WO) + (size_t)l * D * D, scr, r / 32, r % 32, lane); continue; } r -= I_SQ;
.LBB0_37:
	s_andn2_b64 vcc, exec, s[0:1]
	s_cbranch_vccnz .LBB0_39
	s_and_b32 s0, s45, 0x3fc0
	s_add_i32 s30, s0, 0xffffdb00
	s_and_b32 s0, s43, 0x3e0
	v_or_b32_e32 v2, s0, v1
	v_lshlrev_b32_e32 v10, 2, v2
	v_or_b32_e32 v2, s30, v8
	v_lshl_add_u64 v[24:25], s[22:23], 0, v[10:11]
	v_lshlrev_b32_e32 v10, 10, v2
	v_lshl_add_u64 v[2:3], v[10:11], 2, v[24:25]
	global_load_dwordx4 v[88:91], v[2:3], off
	v_or_b32_e32 v10, s30, v28
	v_lshlrev_b32_e32 v10, 10, v10
	v_lshl_add_u64 v[26:27], v[10:11], 2, v[24:25]
	v_or_b32_e32 v10, s30, v29
	v_lshlrev_b32_e32 v10, 10, v10
	v_or_b32_e32 v51, s0, v30
	global_load_dwordx4 v[92:95], v[26:27], off
	v_lshl_add_u64 v[26:27], v[10:11], 2, v[24:25]
	v_or_b32_e32 v10, s30, v30
	v_lshlrev_b32_e32 v10, 10, v10
	global_load_dwordx4 v[96:99], v[26:27], off
	v_lshl_add_u64 v[26:27], v[10:11], 2, v[24:25]
	v_or_b32_e32 v10, s30, v31
	v_lshlrev_b32_e32 v10, 10, v10
	global_load_dwordx4 v[100:103], v[26:27], off
	v_lshl_add_u64 v[26:27], v[10:11], 2, v[24:25]
	v_or_b32_e32 v10, s30, v32
	v_lshlrev_b32_e32 v10, 10, v10
	global_load_dwordx4 v[104:107], v[26:27], off
	v_lshl_add_u64 v[26:27], v[10:11], 2, v[24:25]
	v_or_b32_e32 v10, s30, v33
	v_lshlrev_b32_e32 v10, 10, v10
	global_load_dwordx4 v[108:111], v[26:27], off
	v_lshl_add_u64 v[26:27], v[10:11], 2, v[24:25]
	v_or_b32_e32 v10, s30, v34
	v_lshlrev_b32_e32 v10, 10, v10
	v_lshl_add_u64 v[24:25], v[10:11], 2, v[24:25]
	v_or_b32_e32 v10, s0, v8
	v_lshlrev_b32_e32 v10, 11, v10
	global_load_dwordx4 v[112:115], v[26:27], off
	v_or_b32_e32 v26, s0, v28
	v_or_b32_e32 v27, s0, v29
	global_load_dwordx4 v[116:119], v[24:25], off
	v_lshl_add_u64 v[24:25], s[30:31], 1, v[18:19]
	v_lshl_add_u64 v[60:61], v[24:25], 0, v[10:11]
	v_lshlrev_b32_e32 v10, 11, v26
	v_lshl_add_u64 v[62:63], v[24:25], 0, v[10:11]
	v_lshlrev_b32_e32 v10, 11, v27
	v_lshl_add_u64 v[64:65], v[24:25], 0, v[10:11]
	v_lshlrev_b32_e32 v10, 11, v51
	v_lshl_add_u64 v[66:67], v[24:25], 0, v[10:11]
	s_waitcnt vmcnt(0)
	ds_write2_b32 v36, v88, v89 offset1:1
	ds_write2_b32 v36, v90, v91 offset0:2 offset1:3
	ds_write2_b32 v37, v92, v93 offset1:1
	ds_write2_b32 v38, v94, v95 offset1:1
	ds_write2_b32 v39, v96, v97 offset1:1
	ds_write2_b32 v40, v98, v99 offset1:1
	ds_write2_b32 v41, v100, v101 offset1:1
	ds_write2_b32 v42, v102, v103 offset1:1
	ds_write2_b32 v43, v104, v105 offset1:1
	ds_write2_b32 v44, v106, v107 offset1:1
	ds_write2_b32 v45, v108, v109 offset1:1
	ds_write2_b32 v46, v110, v111 offset1:1
	ds_write2_b32 v47, v112, v113 offset1:1
	ds_write2_b32 v48, v114, v115 offset1:1
	ds_write2_b32 v49, v116, v117 offset1:1
	ds_write2_b32 v50, v118, v119 offset1:1
	s_waitcnt lgkmcnt(0)
	ds_read2_b32 v[24:25], v35 offset0:33 offset1:41
	ds_read2_b32 v[26:27], v35 offset1:8
	ds_read2_b32 v[52:53], v35 offset0:66 offset1:74
	ds_read2_b32 v[54:55], v35 offset0:99 offset1:107
	ds_read2_b32 v[56:57], v35 offset0:132 offset1:140
	ds_read2_b32 v[58:59], v35 offset0:165 offset1:173
	ds_read2_b32 v[68:69], v35 offset0:198 offset1:206
	ds_read2_b32 v[70:71], v35 offset0:231 offset1:239
	ds_read2_b32 v[72:73], v35 offset0:49 offset1:57
	ds_read2_b32 v[74:75], v35 offset0:16 offset1:24
	ds_read2_b32 v[76:77], v35 offset0:82 offset1:90
	ds_read2_b32 v[78:79], v35 offset0:115 offset1:123
	ds_read2_b32 v[80:81], v35 offset0:148 offset1:156
	ds_read2_b32 v[82:83], v35 offset0:181 offset1:189
	ds_read2_b32 v[84:85], v35 offset0:214 offset1:222
	ds_read2_b32 v[86:87], v35 offset0:247 offset1:255
	s_waitcnt lgkmcnt(14)
	v_cvt_pk_bf16_f32 v2, v26, v24
	s_waitcnt lgkmcnt(12)
	v_cvt_pk_bf16_f32 v3, v52, v54
	s_waitcnt lgkmcnt(10)
	v_cvt_pk_bf16_f32 v4, v56, v58
	s_waitcnt lgkmcnt(8)
	v_cvt_pk_bf16_f32 v5, v68, v70
	v_cvt_pk_bf16_f32 v24, v27, v25
	v_cvt_pk_bf16_f32 v25, v53, v55
	v_cvt_pk_bf16_f32 v26, v57, v59
	v_cvt_pk_bf16_f32 v27, v69, v71
	s_waitcnt lgkmcnt(6)
	v_cvt_pk_bf16_f32 v52, v74, v72
	s_waitcnt lgkmcnt(4)
	v_cvt_pk_bf16_f32 v53, v76, v78
	s_waitcnt lgkmcnt(2)
	v_cvt_pk_bf16_f32 v54, v80, v82
	s_waitcnt lgkmcnt(0)
	v_cvt_pk_bf16_f32 v55, v84, v86
	v_cvt_pk_bf16_f32 v56, v75, v73
	v_cvt_pk_bf16_f32 v57, v77, v79
	v_cvt_pk_bf16_f32 v58, v81, v83
	v_cvt_pk_bf16_f32 v59, v85, v87
	global_store_dwordx4 v[60:61], v[2:5], off
	global_store_dwordx4 v[62:63], v[24:27], off
	global_store_dwordx4 v[64:65], v[52:55], off
	global_store_dwordx4 v[66:67], v[56:59], off
	s_waitcnt lgkmcnt(0)

; #define LAS __attribute__((address_space(3)))
; __device__ __forceinline__ unsigned pk2(float lo, float hi) { f32x2 v = {lo, hi}; bf16x2_t b = __builtin_convertvector(v, bf16x2_t); return __builtin_bit_cast(unsigned, b); }
; #define WAVE_LDS_FENCE() asm volatile("s_waitcnt lgkmcnt(0)" ::: "memory")
; template <int MODE>
; __device__ __forceinline__ void transpose_item(const float* W, int K, int Nsrc, const float* g, bf16_t* WT, LAS float* scr, int kb, int nb, int lane) {
;     ...
;     for (int i = 0; i < 8; ++i) { const int kk = 8 * i + (lane >> 3); f32x4 v = {0.f, 0.f, 0.f, 0.f};
;         if (src >= 0) { v = *(const f32x4*)(W + (size_t)(k0 + kk) * Nsrc + src); if (g) v = v * g[k0 + kk]; }
;         LAS float* d = scr + kk * 33 + (lane & 7) * 4; d[0] = v[0]; d[1] = v[1]; d[2] = v[2]; d[3] = v[3]; }
;     WAVE_LDS_FENCE();
;     const int c = lane & 7;
; #pragma unroll
;     for (int j = 0; j < 4; ++j) { const int n = (lane >> 3) + 8 * j; const LAS float* s = scr + (8 * c) * 33 + n;
;         u32x4 o; o.x = pk2(s[0 * 33], s[1 * 33]); o.y = pk2(s[2 * 33], s[3 * 33]); o.z = pk2(s[4 * 33], s[5 * 33]); o.w = pk2(s[6 * 33], s[7 * 33]);
;         *(u32x4*)(WT + (size_t)(n0 + n) * K + k0 + 8 * c) = o; }
;     WAVE_LDS_FENCE();
; __device__ __forceinline__ void prep_weights(const Ctx& P, LAS unsigned char* lds, int l, int gw, int NGW) {
;     ...
;         if (r < I_SQ) { transpose_item<0>(p_wb + (size_t)l * D * D, D, D, nullptr, (bf16_t*)(ws + WS_WB) + (size_t)l * D * D, scr, r / 32, r % 32, lane); continue; } r -= I_SQ;
.LBB0_40:
	s_andn2_b64 vcc, exec, s[0:1]
	s_cbranch_vccnz .LBB0_42
	s_and_b32 s0, s45, 0x3fc0
	s_add_i32 s30, s0, 0xffffdf00
	s_and_b32 s0, s43, 0x3e0
	v_or_b32_e32 v2, s0, v1
	v_lshlrev_b32_e32 v10, 2, v2
	v_or_b32_e32 v2, s30, v8
	v_lshl_add_u64 v[24:25], s[18:19], 0, v[10:11]
	v_lshlrev_b32_e32 v10, 10, v2
	v_lshl_add_u64 v[2:3], v[10:11], 2, v[24:25]
	global_load_dwordx4 v[88:91], v[2:3], off
	v_or_b32_e32 v10, s30, v28
	v_lshlrev_b32_e32 v10, 10, v10
	v_lshl_add_u64 v[26:27], v[10:11], 2, v[24:25]
	v_or_b32_e32 v10, s30, v29
	v_lshlrev_b32_e32 v10, 10, v10
	v_or_b32_e32 v51, s0, v30
	global_load_dwordx4 v[92:95], v[26:27], off
	v_lshl_add_u64 v[26:27], v[10:11], 2, v[24:25]
	v_or_b32_e32 v10, s30, v30
	v_lshlrev_b32_e32 v10, 10, v10
	global_load_dwordx4 v[96:99], v[26:27], off
	v_lshl_add_u64 v[26:27], v[10:11], 2, v[24:25]
	v_or_b32_e32 v10, s30, v31
	v_lshlrev_b32_e32 v10, 10, v10
	global_load_dwordx4 v[100:103], v[26:27], off
	v_lshl_add_u64 v[26:27], v[10:11], 2, v[24:25]
	v_or_b32_e32 v10, s30, v32
	v_lshlrev_b32_e32 v10, 10, v10
	global_load_dwordx4 v[104:107], v[26:27], off
	v_lshl_add_u64 v[26:27], v[10:11], 2, v[24:25]
	v_or_b32_e32 v10, s30, v33
	v_lshlrev_b32_e32 v10, 10, v10
	global_load_dwordx4 v[108:111], v[26:27], off
	v_lshl_add_u64 v[26:27], v[10:11], 2, v[24:25]
	v_or_b32_e32 v10, s30, v34
	v_lshlrev_b32_e32 v10, 10, v10
	v_lshl_add_u64 v[24:25], v[10:11], 2, v[24:25]
	v_or_b32_e32 v10, s0, v8
	v_lshlrev_b32_e32 v10, 11, v10
	global_load_dwordx4 v[112:115], v[26:27], off
	v_or_b32_e32 v26, s0, v28
	v_or_b32_e32 v27, s0, v29
	global_load_dwordx4 v[116:119], v[24:25], off
	v_lshl_add_u64 v[24:25], s[30:31], 1, v[20:21]
	v_lshl_add_u64 v[60:61], v[24:25], 0, v[10:11]
	v_lshlrev_b32_e32 v10, 11, v26
	v_lshl_add_u64 v[62:63], v[24:25], 0, v[10:11]
	v_lshlrev_b32_e32 v10, 11, v27
	v_lshl_add_u64 v[64:65], v[24:25], 0, v[10:11]
	v_lshlrev_b32_e32 v10, 11, v51
	v_lshl_add_u64 v[66:67], v[24:25], 0, v[10:11]
	s_waitcnt vmcnt(0)
	ds_write2_b32 v36, v88, v89 offset1:1
	ds_write2_b32 v36, v90, v91 offset0:2 offset1:3
	ds_write2_b32 v37, v92, v93 offset1:1
	ds_write2_b32 v38, v94, v95 offset1:1
	ds_write2_b32 v39, v96, v97 offset1:1
	ds_write2_b32 v40, v98, v99 offset1:1
	ds_write2_b32 v41, v100, v101 offset1:1
	ds_write2_b32 v42, v102, v103 offset1:1
	ds_write2_b32 v43, v104, v105 offset1:1
	ds_write2_b32 v44, v106, v107 offset1:1
	ds_write2_b32 v45, v108, v109 offset1:1
	ds_write2_b32 v46, v110, v111 offset1:1
	ds_write2_b32 v47, v112, v113 offset1:1
	ds_write2_b32 v48, v114, v115 offset1:1
	ds_write2_b32 v49, v116, v117 offset1:1
	ds_write2_b32 v50, v118, v119 offset1:1
	s_waitcnt lgkmcnt(0)
	ds_read2_b32 v[24:25], v35 offset0:33 offset1:41
	ds_read2_b32 v[26:27], v35 offset1:8
	ds_read2_b32 v[52:53], v35 offset0:66 offset1:74
	ds_read2_b32 v[54:55], v35 offset0:99 offset1:107
	ds_read2_b32 v[56:57], v35 offset0:132 offset1:140
	ds_read2_b32 v[58:59], v35 offset0:165 offset1:173
	ds_read2_b32 v[68:69], v35 offset0:198 offset1:206
	ds_read2_b32 v[70:71], v35 offset0:231 offset1:239
	ds_read2_b32 v[72:73], v35 offset0:49 offset1:57
	ds_read2_b32 v[74:75], v35 offset0:16 offset1:24
	ds_read2_b32 v[76:77], v35 offset0:82 offset1:90
	ds_read2_b32 v[78:79], v35 offset0:115 offset1:123
	ds_read2_b32 v[80:81], v35 offset0:148 offset1:156
	ds_read2_b32 v[82:83], v35 offset0:181 offset1:189
	ds_read2_b32 v[84:85], v35 offset0:214 offset1:222
	ds_read2_b32 v[86:87], v35 offset0:247 offset1:255
	s_waitcnt lgkmcnt(14)
	v_cvt_pk_bf16_f32 v2, v26, v24
	s_waitcnt lgkmcnt(12)
	v_cvt_pk_bf16_f32 v3, v52, v54
	s_waitcnt lgkmcnt(10)
	v_cvt_pk_bf16_f32 v4, v56, v58
	s_waitcnt lgkmcnt(8)
	v_cvt_pk_bf16_f32 v5, v68, v70
	v_cvt_pk_bf16_f32 v24, v27, v25
	v_cvt_pk_bf16_f32 v25, v53, v55
	v_cvt_pk_bf16_f32 v26, v57, v59
	v_cvt_pk_bf16_f32 v27, v69, v71
	s_waitcnt lgkmcnt(6)
	v_cvt_pk_bf16_f32 v52, v74, v72
	s_waitcnt lgkmcnt(4)
	v_cvt_pk_bf16_f32 v53, v76, v78
	s_waitcnt lgkmcnt(2)
	v_cvt_pk_bf16_f32 v54, v80, v82
	s_waitcnt lgkmcnt(0)
	v_cvt_pk_bf16_f32 v55, v84, v86
	v_cvt_pk_bf16_f32 v56, v75, v73
	v_cvt_pk_bf16_f32 v57, v77, v79
	v_cvt_pk_bf16_f32 v58, v81, v83
	v_cvt_pk_bf16_f32 v59, v85, v87
	global_store_dwordx4 v[60:61], v[2:5], off
	global_store_dwordx4 v[62:63], v[24:27], off
	global_store_dwordx4 v[64:65], v[52:55], off
	global_store_dwordx4 v[66:67], v[56:59], off
	s_waitcnt lgkmcnt(0)

; #define LAS __attribute__((address_space(3)))
; __device__ __forceinline__ unsigned pk2(float lo, float hi) { f32x2 v = {lo, hi}; bf16x2_t b = __builtin_convertvector(v, bf16x2_t); return __builtin_bit_cast(unsigned, b); }
; #define WAVE_LDS_FENCE() asm volatile("s_waitcnt lgkmcnt(0)" ::: "memory")
; template <int MODE>
; __device__ __forceinline__ void transpose_item(const float* W, int K, int Nsrc, const float* g, bf16_t* WT, LAS float* scr, int kb, int nb, int lane) {
;     ...
;     for (int i = 0; i < 8; ++i) { const int kk = 8 * i + (lane >> 3); f32x4 v = {0.f, 0.f, 0.f, 0.f};
;         if (src >= 0) { v = *(const f32x4*)(W + (size_t)(k0 + kk) * Nsrc + src); if (g) v = v * g[k0 + kk]; }
;         LAS float* d = scr + kk * 33 + (lane & 7) * 4; d[0] = v[0]; d[1] = v[1]; d[2] = v[2]; d[3] = v[3]; }
;     WAVE_LDS_FENCE();
;     const int c = lane & 7;
; #pragma unroll
;     for (int j = 0; j < 4; ++j) { const int n = (lane >> 3) + 8 * j; const LAS float* s = scr + (8 * c) * 33 + n;
;         u32x4 o; o.x = pk2(s[0 * 33], s[1 * 33]); o.y = pk2(s[2 * 33], s[3 * 33]); o.z = pk2(s[4 * 33], s[5 * 33]); o.w = pk2(s[6 * 33], s[7 * 33]);
;         *(u32x4*)(WT + (size_t)(n0 + n) * K + k0 + 8 * c) = o; }
;     WAVE_LDS_FENCE();
; __device__ __forceinline__ void prep_weights(const Ctx& P, LAS unsigned char* lds, int l, int gw, int NGW) {
;     ...
;         if (r < I_SQ) { transpose_item<0>(p_wa + (size_t)l * D * D, D, D, nullptr, (bf16_t*)(ws + WS_WA) + (size_t)l * D * D, scr, r / 32, r % 32, lane); continue; } r -= I_SQ;
.LBB0_43:
	s_andn2_b64 vcc, exec, s[0:1]
	s_cbranch_vccnz .LBB0_45
	s_and_b32 s0, s45, 0x3fc0
	s_add_i32 s30, s0, 0xffffe300
	s_and_b32 s0, s43, 0x3e0
	v_or_b32_e32 v2, s0, v1
	v_lshlrev_b32_e32 v10, 2, v2
	v_or_b32_e32 v2, s30, v8
	v_lshl_add_u64 v[24:25], s[16:17], 0, v[10:11]
	v_lshlrev_b32_e32 v10, 10, v2
	v_lshl_add_u64 v[2:3], v[10:11], 2, v[24:25]
	global_load_dwordx4 v[88:91], v[2:3], off
	v_or_b32_e32 v10, s30, v28
	v_lshlrev_b32_e32 v10, 10, v10
	v_lshl_add_u64 v[26:27], v[10:11], 2, v[24:25]
	v_or_b32_e32 v10, s30, v29
	v_lshlrev_b32_e32 v10, 10, v10
	v_or_b32_e32 v51, s0, v30
	global_load_dwordx4 v[92:95], v[26:27], off
	v_lshl_add_u64 v[26:27], v[10:11], 2, v[24:25]
	v_or_b32_e32 v10, s30, v30
	v_lshlrev_b32_e32 v10, 10, v10
	global_load_dwordx4 v[96:99], v[26:27], off
	v_lshl_add_u64 v[26:27], v[10:11], 2, v[24:25]
	v_or_b32_e32 v10, s30, v31
	v_lshlrev_b32_e32 v10, 10, v10
	global_load_dwordx4 v[100:103], v[26:27], off
	v_lshl_add_u64 v[26:27], v[10:11], 2, v[24:25]
	v_or_b32_e32 v10, s30, v32
	v_lshlrev_b32_e32 v10, 10, v10
	global_load_dwordx4 v[104:107], v[26:27], off
	v_lshl_add_u64 v[26:27], v[10:11], 2, v[24:25]
	v_or_b32_e32 v10, s30, v33
	v_lshlrev_b32_e32 v10, 10, v10
	global_load_dwordx4 v[108:111], v[26:27], off
	v_lshl_add_u64 v[26:27], v[10:11], 2, v[24:25]
	v_or_b32_e32 v10, s30, v34
	v_lshlrev_b32_e32 v10, 10, v10
	v_lshl_add_u64 v[24:25], v[10:11], 2, v[24:25]
	v_or_b32_e32 v10, s0, v8
	v_lshlrev_b32_e32 v10, 11, v10
	global_load_dwordx4 v[112:115], v[26:27], off
	v_or_b32_e32 v26, s0, v28
	v_or_b32_e32 v27, s0, v29
	global_load_dwordx4 v[116:119], v[24:25], off
	v_lshl_add_u64 v[24:25], s[30:31], 1, v[22:23]
	v_lshl_add_u64 v[60:61], v[24:25], 0, v[10:11]
	v_lshlrev_b32_e32 v10, 11, v26
	v_lshl_add_u64 v[62:63], v[24:25], 0, v[10:11]
	v_lshlrev_b32_e32 v10, 11, v27
	v_lshl_add_u64 v[64:65], v[24:25], 0, v[10:11]
	v_lshlrev_b32_e32 v10, 11, v51
	v_lshl_add_u64 v[66:67], v[24:25], 0, v[10:11]
	s_waitcnt vmcnt(0)
	ds_write2_b32 v36, v88, v89 offset1:1
	ds_write2_b32 v36, v90, v91 offset0:2 offset1:3
	ds_write2_b32 v37, v92, v93 offset1:1
	ds_write2_b32 v38, v94, v95 offset1:1
	ds_write2_b32 v39, v96, v97 offset1:1
	ds_write2_b32 v40, v98, v99 offset1:1
	ds_write2_b32 v41, v100, v101 offset1:1
	ds_write2_b32 v42, v102, v103 offset1:1
	ds_write2_b32 v43, v104, v105 offset1:1
	ds_write2_b32 v44, v106, v107 offset1:1
	ds_write2_b32 v45, v108, v109 offset1:1
	ds_write2_b32 v46, v110, v111 offset1:1
	ds_write2_b32 v47, v112, v113 offset1:1
	ds_write2_b32 v48, v114, v115 offset1:1
	ds_write2_b32 v49, v116, v117 offset1:1
	ds_write2_b32 v50, v118, v119 offset1:1
	s_waitcnt lgkmcnt(0)
	ds_read2_b32 v[4:5], v35 offset0:33 offset1:41
	ds_read2_b32 v[24:25], v35 offset1:8
	ds_read2_b32 v[26:27], v35 offset0:66 offset1:74
	ds_read2_b32 v[52:53], v35 offset0:99 offset1:107
	ds_read2_b32 v[54:55], v35 offset0:132 offset1:140
	ds_read2_b32 v[56:57], v35 offset0:165 offset1:173
	ds_read2_b32 v[58:59], v35 offset0:198 offset1:206
	ds_read2_b32 v[68:69], v35 offset0:231 offset1:239
	ds_read2_b32 v[70:71], v35 offset0:49 offset1:57
	ds_read2_b32 v[72:73], v35 offset0:16 offset1:24
	ds_read2_b32 v[74:75], v35 offset0:82 offset1:90
	ds_read2_b32 v[76:77], v35 offset0:115 offset1:123
	ds_read2_b32 v[78:79], v35 offset0:148 offset1:156
	ds_read2_b32 v[80:81], v35 offset0:181 offset1:189
	ds_read2_b32 v[82:83], v35 offset0:214 offset1:222
	ds_read2_b32 v[84:85], v35 offset0:247 offset1:255
	s_waitcnt lgkmcnt(14)
	v_cvt_pk_bf16_f32 v2, v24, v4
	s_waitcnt lgkmcnt(12)
	v_cvt_pk_bf16_f32 v3, v26, v52
	v_cvt_pk_bf16_f32 v24, v25, v5
	s_waitcnt lgkmcnt(10)
	v_cvt_pk_bf16_f32 v4, v54, v56
	s_waitcnt lgkmcnt(8)
	v_cvt_pk_bf16_f32 v5, v58, v68
	v_cvt_pk_bf16_f32 v25, v27, v53
	v_cvt_pk_bf16_f32 v26, v55, v57
	v_cvt_pk_bf16_f32 v27, v59, v69
	s_waitcnt lgkmcnt(6)
	v_cvt_pk_bf16_f32 v52, v72, v70
	s_waitcnt lgkmcnt(4)
	v_cvt_pk_bf16_f32 v53, v74, v76
	s_waitcnt lgkmcnt(2)
	v_cvt_pk_bf16_f32 v54, v78, v80
	s_waitcnt lgkmcnt(0)
	v_cvt_pk_bf16_f32 v55, v82, v84
	v_cvt_pk_bf16_f32 v56, v73, v71
	v_cvt_pk_bf16_f32 v57, v75, v77
	v_cvt_pk_bf16_f32 v58, v79, v81
	v_cvt_pk_bf16_f32 v59, v83, v85
	global_store_dwordx4 v[60:61], v[2:5], off
	global_store_dwordx4 v[62:63], v[24:27], off
	global_store_dwordx4 v[64:65], v[52:55], off
	global_store_dwordx4 v[66:67], v[56:59], off
	s_waitcnt lgkmcnt(0)

; #define LAS __attribute__((address_space(3)))
; template <int MODE>
; __device__ __forceinline__ void transpose_item(const float* W, int K, int Nsrc, const float* g, bf16_t* WT, LAS float* scr, int kb, int nb, int lane) {
;     ...
;     int src = nd;
;     if (MODE == 1) src = nd < 4096 ? nd : (nd < 7168 ? nd + 16 : (nd < 7184 ? nd - 7168 + 4096 : -1));
; #pragma unroll
;     for (int i = 0; i < 8; ++i) { const int kk = 8 * i + (lane >> 3); f32x4 v = {0.f, 0.f, 0.f, 0.f};
;         if (src >= 0) { v = *(const f32x4*)(W + (size_t)(k0 + kk) * Nsrc + src); if (g) v = v * g[k0 + kk]; }
;         LAS float* d = scr + kk * 33 + (lane & 7) * 4; d[0] = v[0]; d[1] = v[1]; d[2] = v[2]; d[3] = v[3]; }
; __device__ __forceinline__ void prep_weights(const Ctx& P, LAS unsigned char* lds, int l, int gw, int NGW) {
;     ...
;         if (r < I_IN) { transpose_item<1>(p_win + (size_t)l * D * 7184, D, 7184, p_g1 + l * D, (bf16_t*)(ws + WS_WIN) + (size_t)l * NZ * D, scr, r / 232, r % 232, lane); continue; } r -= I_IN;
.LBB0_52:
	s_or_b64 exec, exec, s[0:1]
	v_cmp_gt_i32_e64 s[4:5], 0, v10
	v_cndmask_b32_e64 v2, 0, 1, s[36:37]
	s_lshl_b32 s38, s38, 6
	v_lshl_add_u64 v[24:25], v[10:11], 2, s[12:13]
	v_cmp_ne_u32_e64 s[0:1], 1, v2
	v_mov_b32_e32 v88, 0
	v_mov_b32_e32 v89, 0
	v_mov_b32_e32 v90, 0
	v_mov_b32_e32 v91, 0
	v_mov_b32_e32 v92, 0
	v_mov_b32_e32 v93, 0
	v_mov_b32_e32 v94, 0
	v_mov_b32_e32 v95, 0
	v_mov_b32_e32 v96, 0
	v_mov_b32_e32 v97, 0
	v_mov_b32_e32 v98, 0
	v_mov_b32_e32 v99, 0
	v_mov_b32_e32 v100, 0
	v_mov_b32_e32 v101, 0
	v_mov_b32_e32 v102, 0
	v_mov_b32_e32 v103, 0
	v_mov_b32_e32 v104, 0
	v_mov_b32_e32 v105, 0
	v_mov_b32_e32 v106, 0
	v_mov_b32_e32 v107, 0
	v_mov_b32_e32 v108, 0
	v_mov_b32_e32 v109, 0
	v_mov_b32_e32 v110, 0
	v_mov_b32_e32 v111, 0
	v_mov_b32_e32 v112, 0
	v_mov_b32_e32 v113, 0
	v_mov_b32_e32 v114, 0
	v_mov_b32_e32 v115, 0
	v_mov_b32_e32 v116, 0
	v_mov_b32_e32 v117, 0
	v_mov_b32_e32 v118, 0
	v_mov_b32_e32 v119, 0
	s_mov_b64 s[40:41], exec
	s_andn2_b64 exec, exec, s[4:5]
	s_cbranch_execz .Lpw_in_wr
	v_or_b32_e32 v2, s38, v8
	v_mad_i64_i32 v[2:3], vcc, v2, s49, v[24:25]
	global_load_dwordx4 v[88:91], v[2:3], off
	v_or_b32_e32 v2, s38, v28
	v_mad_i64_i32 v[2:3], vcc, v2, s49, v[24:25]
	global_load_dwordx4 v[92:95], v[2:3], off
	v_or_b32_e32 v2, s38, v29
	v_mad_i64_i32 v[2:3], vcc, v2, s49, v[24:25]
	global_load_dwordx4 v[96:99], v[2:3], off
	v_or_b32_e32 v2, s38, v30
	v_mad_i64_i32 v[2:3], vcc, v2, s49, v[24:25]
	global_load_dwordx4 v[100:103], v[2:3], off
	v_or_b32_e32 v2, s38, v31
	v_mad_i64_i32 v[2:3], vcc, v2, s49, v[24:25]
	global_load_dwordx4 v[104:107], v[2:3], off
	v_or_b32_e32 v2, s38, v32
	v_mad_i64_i32 v[2:3], vcc, v2, s49, v[24:25]
	global_load_dwordx4 v[108:111], v[2:3], off
	v_or_b32_e32 v2, s38, v33
	v_mad_i64_i32 v[2:3], vcc, v2, s49, v[24:25]
	global_load_dwordx4 v[112:115], v[2:3], off
	v_or_b32_e32 v2, s38, v34
	v_mad_i64_i32 v[2:3], vcc, v2, s49, v[24:25]
	global_load_dwordx4 v[116:119], v[2:3], off
	s_and_b64 vcc, exec, s[0:1]
	s_cbranch_vccnz .Lpw_in_wait
	s_ashr_i32 s39, s38, 31
	v_lshl_add_u64 v[26:27], s[38:39], 0, v[8:9]
	v_lshl_add_u64 v[26:27], v[26:27], 2, s[14:15]
	global_load_dword v144, v[26:27], off
	global_load_dword v146, v[26:27], off offset:32
	global_load_dword v148, v[26:27], off offset:64
	global_load_dword v150, v[26:27], off offset:96
	global_load_dword v152, v[26:27], off offset:128
	global_load_dword v154, v[26:27], off offset:160
	global_load_dword v156, v[26:27], off offset:192
	global_load_dword v158, v[26:27], off offset:224
	s_waitcnt vmcnt(0)
	v_pk_mul_f32 v[90:91], v[90:91], v[144:145] op_sel_hi:[1,0]
	v_pk_mul_f32 v[88:89], v[88:89], v[144:145] op_sel_hi:[1,0]
	v_pk_mul_f32 v[94:95], v[94:95], v[146:147] op_sel_hi:[1,0]
	v_pk_mul_f32 v[92:93], v[92:93], v[146:147] op_sel_hi:[1,0]
	v_pk_mul_f32 v[98:99], v[98:99], v[148:149] op_sel_hi:[1,0]
	v_pk_mul_f32 v[96:97], v[96:97], v[148:149] op_sel_hi:[1,0]
	v_pk_mul_f32 v[102:103], v[102:103], v[150:151] op_sel_hi:[1,0]
	v_pk_mul_f32 v[100:101], v[100:101], v[150:151] op_sel_hi:[1,0]
	v_pk_mul_f32 v[106:107], v[106:107], v[152:153] op_sel_hi:[1,0]
	v_pk_mul_f32 v[104:105], v[104:105], v[152:153] op_sel_hi:[1,0]
	v_pk_mul_f32 v[110:111], v[110:111], v[154:155] op_sel_hi:[1,0]
	v_pk_mul_f32 v[108:109], v[108:109], v[154:155] op_sel_hi:[1,0]
	v_pk_mul_f32 v[114:115], v[114:115], v[156:157] op_sel_hi:[1,0]
	v_pk_mul_f32 v[112:113], v[112:113], v[156:157] op_sel_hi:[1,0]
	v_pk_mul_f32 v[118:119], v[118:119], v[158:159] op_sel_hi:[1,0]
	v_pk_mul_f32 v[116:117], v[116:117], v[158:159] op_sel_hi:[1,0]

; #define LAS __attribute__((address_space(3)))
; #define WAVE_LDS_FENCE() asm volatile("s_waitcnt lgkmcnt(0)" ::: "memory")
; template <int MODE>
; __device__ __forceinline__ void transpose_item(const float* W, int K, int Nsrc, const float* g, bf16_t* WT, LAS float* scr, int kb, int nb, int lane) {
;     ...
;     for (int i = 0; i < 8; ++i) { const int kk = 8 * i + (lane >> 3); f32x4 v = {0.f, 0.f, 0.f, 0.f};
;         if (src >= 0) { v = *(const f32x4*)(W + (size_t)(k0 + kk) * Nsrc + src); if (g) v = v * g[k0 + kk]; }
;         LAS float* d = scr + kk * 33 + (lane & 7) * 4; d[0] = v[0]; d[1] = v[1]; d[2] = v[2]; d[3] = v[3]; }
;     WAVE_LDS_FENCE();
.Lpw_in_wr:
	s_mov_b64 exec, s[40:41]
	ds_write2_b32 v36, v88, v89 offset1:1
	ds_write2_b32 v36, v90, v91 offset0:2 offset1:3
	ds_write2_b32 v37, v92, v93 offset1:1
	ds_write2_b32 v38, v94, v95 offset1:1
	ds_write2_b32 v39, v96, v97 offset1:1
	ds_write2_b32 v40, v98, v99 offset1:1
	ds_write2_b32 v41, v100, v101 offset1:1
	ds_write2_b32 v42, v102, v103 offset1:1
	ds_write2_b32 v43, v104, v105 offset1:1
	ds_write2_b32 v44, v106, v107 offset1:1
	ds_write2_b32 v45, v108, v109 offset1:1
	ds_write2_b32 v46, v110, v111 offset1:1
	ds_write2_b32 v47, v112, v113 offset1:1
	ds_write2_b32 v48, v114, v115 offset1:1
	ds_write2_b32 v49, v116, v117 offset1:1
	ds_write2_b32 v50, v118, v119 offset1:1
	s_branch .LBB0_10
